# barrier0-compact_and_no-inv-in-rowstat-exchange
# speedup vs baseline: 1.0206x; 1.0040x over previous
; __device__ __forceinline__ unsigned xb_ld(unsigned* p)              { return __hip_atomic_load(p, __ATOMIC_RELAXED, __HIP_MEMORY_SCOPE_AGENT); }
; __device__ __forceinline__ unsigned xb_add(unsigned* p, unsigned v) { return __hip_atomic_fetch_add(p, v, __ATOMIC_RELAXED, __HIP_MEMORY_SCOPE_AGENT); }
; #define X make_ctx(lds_raw)
; __device__ __forceinline__ void xcd_barrier(const XcdBarrier& b) {
;     asm volatile("s_waitcnt vmcnt(0)" ::: "memory");
;     __syncthreads();
;     if (threadIdx.x == 0) {
;         unsigned* bar = b.bar;
;         __builtin_amdgcn_s_waitcnt(0);
;         unsigned nloc = b.st[0], nx = b.st[1];
;         if (nloc == 0u) { xcd_barrier_complete(bar, b.x, nloc, nx); b.st[0] = nloc; b.st[1] = nx; }
;         const unsigned old = xb_add(&bar[XB_XSUB(b.x)], 1u);
;         const unsigned gen = old / nloc;
;         if (old + 1u == (gen + 1u) * nloc) {
;             __builtin_amdgcn_fence(__ATOMIC_RELEASE, "agent");
;             asm volatile("s_waitcnt vmcnt(0)" ::: "memory");
;             const unsigned og = xb_add(&bar[XB_TOP], 1u);
;             const unsigned tg = og / nx;
;             if (og + 1u == (tg + 1u) * nx) xb_add(&bar[XB_TOPGEN], 1u);
;             else XB_SPIN(xb_ld(&bar[XB_TOPGEN]) == tg, bar);
;             __builtin_amdgcn_fence(__ATOMIC_ACQUIRE, "agent");
;             xb_add(&bar[XB_XGEN(b.x)], 1u);
;             asm volatile("s_waitcnt vmcnt(0)" ::: "memory");
;         } else {
;             XB_SPIN(xb_ld(&bar[XB_XGEN(b.x)]) == gen, bar);
;             __builtin_amdgcn_fence(__ATOMIC_ACQUIRE, "agent");
;             asm volatile("s_waitcnt vmcnt(0)" ::: "memory");
;         }
;     }
;     __syncthreads();
; }
; template <int MODE> __device__ __forceinline__ void norm_pass(const Ctx& X, KArgs a, const float* xin, bf16_t* hout, float* fout) {
;     ...
;     if (MODE == 0) { for (int idx = X.gtid; idx < 4 * 6144; idx += X.nthr) { const int b = idx / 6144, j = idx % 6144; float s = a->ada_b[j];
;             float pv[32];
; #pragma unroll
;             for (int kc = 0; kc < 32; ++kc) pv[kc] = modp[(size_t)(kc * 4 + b) * 6144 + j];
; #pragma unroll
;             for (int kc = 0; kc < 32; ++kc) s += pv[kc];
;             mod[idx] = s; } }
.LBB0_47:
	v_readlane_b32 s98, v254, 5
	v_readlane_b32 s99, v254, 6
	v_readlane_b32 s6, v254, 1
	v_mov_b32_e32 v0, 0x23fc0
	s_waitcnt vmcnt(0) lgkmcnt(0)
	ds_read2_b32 v[2:3], v0 offset1:1
	s_lshl_b32 s6, s6, 8
	s_add_u32 s100, s98, s6
	s_addc_u32 s101, s99, 0
	v_mov_b32_e32 v0, 0x1000
	v_mov_b32_e32 v1, 1
	global_atomic_add v4, v0, v1, s[100:101] offset:1024 sc0
	buffer_inv sc1
	s_waitcnt lgkmcnt(0)
	v_readfirstlane_b32 s2, v2
	v_readfirstlane_b32 s3, v3
	s_mul_i32 s2, s2, 1
	s_mul_i32 s3, s3, 1
	s_waitcnt vmcnt(1)
	v_readfirstlane_b32 s6, v4
	s_add_i32 s6, s6, 1
	s_cmp_lg_u32 s6, s2
	s_cbranch_scc1 .Lxb0_spin
	buffer_wbl2 sc1
	s_waitcnt vmcnt(0)
	v_mov_b32_e32 v0, 0x3000
	global_atomic_add v0, v1, s[98:99] offset:1024
.Lxb0_spin:
	v_mov_b32_e32 v0, 0x3000
	s_mov_b32 s7, 0x200000
.Lxb0_poll:
	global_load_dword v4, v0, s[98:99] offset:1024 sc1
	s_waitcnt vmcnt(0)
	v_readfirstlane_b32 s6, v4
	s_cmp_ge_u32 s6, s3
	s_cbranch_scc1 .Lxb0_done
	s_sleep 1
	s_add_i32 s7, s7, -1
	s_cmp_lg_u32 s7, 0
	s_cbranch_scc1 .Lxb0_poll
.Lxb0_done:
	s_waitcnt vmcnt(0)
.LBB0_83:
	s_or_b64 exec, exec, s[0:1]
	s_mov_b64 s[0:1], s[86:87]
	v_mov_b32_e32 v72, v186
	s_waitcnt lgkmcnt(0)
	s_barrier
	s_load_dwordx2 s[4:5], s[0:1], 0xa0
	v_writelane_b32 v254, s0, 8
	v_readfirstlane_b32 s10, v72
	s_waitcnt lgkmcnt(0)
	s_add_u32 s30, s4, 0x300000
	v_writelane_b32 v254, s1, 9
	s_load_dwordx2 s[0:1], s[0:1], 0x0
	v_readlane_b32 s2, v254, 4
	v_writelane_b32 v254, s4, 10
	s_addc_u32 s31, s5, 0
	v_add_u32_e32 v0, s2, v72
	s_movk_i32 s2, 0x6000
	v_writelane_b32 v254, s5, 11
	v_cmp_gt_i32_e32 vcc, s2, v0
	s_and_saveexec_b64 s[2:3], vcc
	s_cbranch_execz .LBB0_86
	v_readlane_b32 s6, v254, 8
	v_readlane_b32 s7, v254, 9
	s_load_dwordx2 s[6:7], s[6:7], 0x20
	v_readlane_b32 s4, v254, 10
	v_readlane_b32 s5, v254, 11
	s_add_u32 s4, s4, 0x40000
	s_addc_u32 s5, s5, 0
	s_mov_b64 s[8:9], 0
	s_mov_b32 s11, 0x2aaaaaab
	s_movk_i32 s12, 0x5fff

; __device__ __forceinline__ unsigned xb_ld(unsigned* p)              { return __hip_atomic_load(p, __ATOMIC_RELAXED, __HIP_MEMORY_SCOPE_AGENT); }
; __device__ __forceinline__ unsigned xb_add(unsigned* p, unsigned v) { return __hip_atomic_fetch_add(p, v, __ATOMIC_RELAXED, __HIP_MEMORY_SCOPE_AGENT); }
; #define XB_SPIN(cond, bar) do { unsigned _sp = 0; while (cond) { __builtin_amdgcn_s_sleep(1); \
;     if ((++_sp & 255u) == 0u) { if (xb_ld(&(bar)[XB_TMO])) break; if (_sp > XB_SPIN_CAP) { atomicAdd(&(bar)[XB_TMO], 1u); break; } } } } while (0)
; __device__ __forceinline__ void xcd_barrier(const XcdBarrier& b) {
;     ...
;         const unsigned old = xb_add(&bar[XB_XSUB(b.x)], 1u);
;         const unsigned gen = old / nloc;
;         if (old + 1u == (gen + 1u) * nloc) {
;             __builtin_amdgcn_fence(__ATOMIC_RELEASE, "agent");
;             asm volatile("s_waitcnt vmcnt(0)" ::: "memory");
;             const unsigned og = xb_add(&bar[XB_TOP], 1u);
;             const unsigned tg = og / nx;
;             if (og + 1u == (tg + 1u) * nx) xb_add(&bar[XB_TOPGEN], 1u);
;             else XB_SPIN(xb_ld(&bar[XB_TOPGEN]) == tg, bar);
;             __builtin_amdgcn_fence(__ATOMIC_ACQUIRE, "agent");
;             xb_add(&bar[XB_XGEN(b.x)], 1u);
.LBB0_124:
	s_waitcnt vmcnt(0)
	s_barrier
	s_mov_b64 s[0:1], exec
	v_readlane_b32 s2, v254, 2
	v_readlane_b32 s3, v254, 3
	s_and_b64 s[2:3], s[0:1], s[2:3]
	s_mov_b64 exec, s[2:3]
	s_cbranch_execz .LBB0_176
	v_readlane_b32 s98, v254, 5
	v_readlane_b32 s99, v254, 6
	v_readlane_b32 s6, v254, 1
	v_mov_b32_e32 v0, 0x23fc0
	s_waitcnt vmcnt(0) lgkmcnt(0)
	ds_read2_b32 v[2:3], v0 offset1:1
	s_lshl_b32 s6, s6, 8
	s_add_u32 s100, s98, s6
	s_addc_u32 s101, s99, 0
	v_mov_b32_e32 v0, 0x1000
	v_mov_b32_e32 v1, 1
	global_atomic_add v4, v0, v1, s[100:101] offset:1024 sc0
	buffer_inv sc1
	s_waitcnt lgkmcnt(0)
	v_readfirstlane_b32 s2, v2
	v_readfirstlane_b32 s3, v3
	s_mul_i32 s2, s2, 2
	s_mul_i32 s3, s3, 2
	s_waitcnt vmcnt(1)
	v_readfirstlane_b32 s6, v4
	s_add_i32 s6, s6, 1
	s_cmp_lg_u32 s6, s2
	s_cbranch_scc1 .Lxb1_spin
	buffer_wbl2 sc1
	s_waitcnt vmcnt(0)
	v_mov_b32_e32 v0, 0x3000
	global_atomic_add v0, v1, s[98:99] offset:1024

; __device__ __forceinline__ unsigned xb_ld(unsigned* p)              { return __hip_atomic_load(p, __ATOMIC_RELAXED, __HIP_MEMORY_SCOPE_AGENT); }
; __device__ __forceinline__ unsigned xb_add(unsigned* p, unsigned v) { return __hip_atomic_fetch_add(p, v, __ATOMIC_RELAXED, __HIP_MEMORY_SCOPE_AGENT); }
; #define XB_SPIN(cond, bar) do { unsigned _sp = 0; while (cond) { __builtin_amdgcn_s_sleep(1); \
;     if ((++_sp & 255u) == 0u) { if (xb_ld(&(bar)[XB_TMO])) break; if (_sp > XB_SPIN_CAP) { atomicAdd(&(bar)[XB_TMO], 1u); break; } } } } while (0)
; __device__ __forceinline__ void xcd_barrier(const XcdBarrier& b) {
;     ...
;         const unsigned old = xb_add(&bar[XB_XSUB(b.x)], 1u);
;         const unsigned gen = old / nloc;
;         if (old + 1u == (gen + 1u) * nloc) {
;             __builtin_amdgcn_fence(__ATOMIC_RELEASE, "agent");
;             asm volatile("s_waitcnt vmcnt(0)" ::: "memory");
;             const unsigned og = xb_add(&bar[XB_TOP], 1u);
;             const unsigned tg = og / nx;
;             if (og + 1u == (tg + 1u) * nx) xb_add(&bar[XB_TOPGEN], 1u);
;             else XB_SPIN(xb_ld(&bar[XB_TOPGEN]) == tg, bar);
;             __builtin_amdgcn_fence(__ATOMIC_ACQUIRE, "agent");
;             xb_add(&bar[XB_XGEN(b.x)], 1u);
.LBB0_274:
	s_waitcnt vmcnt(0)
	s_waitcnt vmcnt(0)
	s_barrier
	s_mov_b64 s[0:1], exec
	v_readlane_b32 s2, v254, 2
	v_readlane_b32 s3, v254, 3
	s_and_b64 s[2:3], s[0:1], s[2:3]
	s_mov_b64 exec, s[2:3]
	s_cbranch_execz .LBB0_326
	v_readlane_b32 s98, v254, 5
	v_readlane_b32 s99, v254, 6
	v_readlane_b32 s6, v254, 1
	v_mov_b32_e32 v0, 0x23fc0
	s_waitcnt vmcnt(0) lgkmcnt(0)
	ds_read2_b32 v[2:3], v0 offset1:1
	s_lshl_b32 s6, s6, 8
	s_add_u32 s100, s98, s6
	s_addc_u32 s101, s99, 0
	v_mov_b32_e32 v0, 0x1000
	v_mov_b32_e32 v1, 1
	global_atomic_add v4, v0, v1, s[100:101] offset:1024 sc0
	buffer_inv sc1
	s_waitcnt lgkmcnt(0)
	v_readfirstlane_b32 s2, v2
	v_readfirstlane_b32 s3, v3
	s_mul_i32 s2, s2, 3
	s_mul_i32 s3, s3, 3
	s_waitcnt vmcnt(1)
	v_readfirstlane_b32 s6, v4
	s_add_i32 s6, s6, 1
	s_cmp_lg_u32 s6, s2
	s_cbranch_scc1 .Lxb2_spin
	buffer_wbl2 sc1
	s_waitcnt vmcnt(0)
	v_mov_b32_e32 v0, 0x3000
	global_atomic_add v0, v1, s[98:99] offset:1024

; __device__ __forceinline__ unsigned xb_ld(unsigned* p)              { return __hip_atomic_load(p, __ATOMIC_RELAXED, __HIP_MEMORY_SCOPE_AGENT); }
; __device__ __forceinline__ unsigned xb_add(unsigned* p, unsigned v) { return __hip_atomic_fetch_add(p, v, __ATOMIC_RELAXED, __HIP_MEMORY_SCOPE_AGENT); }
; #define XB_SPIN(cond, bar) do { unsigned _sp = 0; while (cond) { __builtin_amdgcn_s_sleep(1); \
;     if ((++_sp & 255u) == 0u) { if (xb_ld(&(bar)[XB_TMO])) break; if (_sp > XB_SPIN_CAP) { atomicAdd(&(bar)[XB_TMO], 1u); break; } } } } while (0)
; __device__ __forceinline__ void xcd_barrier(const XcdBarrier& b) {
;     ...
;         const unsigned old = xb_add(&bar[XB_XSUB(b.x)], 1u);
;         const unsigned gen = old / nloc;
;         if (old + 1u == (gen + 1u) * nloc) {
;             __builtin_amdgcn_fence(__ATOMIC_RELEASE, "agent");
;             asm volatile("s_waitcnt vmcnt(0)" ::: "memory");
;             const unsigned og = xb_add(&bar[XB_TOP], 1u);
;             const unsigned tg = og / nx;
;             if (og + 1u == (tg + 1u) * nx) xb_add(&bar[XB_TOPGEN], 1u);
;             else XB_SPIN(xb_ld(&bar[XB_TOPGEN]) == tg, bar);
;             __builtin_amdgcn_fence(__ATOMIC_ACQUIRE, "agent");
;             xb_add(&bar[XB_XGEN(b.x)], 1u);
.LBB0_343:
	s_waitcnt vmcnt(0)
	s_barrier
	s_mov_b64 s[0:1], exec
	v_readlane_b32 s2, v254, 2
	v_readlane_b32 s3, v254, 3
	v_readlane_b32 s34, v254, 5
	s_and_b64 s[2:3], s[0:1], s[2:3]
	v_readlane_b32 s35, v254, 6
	v_readlane_b32 s36, v254, 17
	v_readlane_b32 s37, v254, 18
	s_mov_b64 exec, s[2:3]
	s_cbranch_execz .LBB0_395
	v_readlane_b32 s98, v254, 5
	v_readlane_b32 s99, v254, 6
	v_readlane_b32 s6, v254, 1
	v_mov_b32_e32 v0, 0x23fc0
	s_waitcnt vmcnt(0) lgkmcnt(0)
	ds_read2_b32 v[2:3], v0 offset1:1
	s_lshl_b32 s6, s6, 8
	s_add_u32 s100, s98, s6
	s_addc_u32 s101, s99, 0
	v_mov_b32_e32 v0, 0x1000
	v_mov_b32_e32 v1, 1
	global_atomic_add v4, v0, v1, s[100:101] offset:1024 sc0
	buffer_inv sc1
	s_waitcnt lgkmcnt(0)
	v_readfirstlane_b32 s2, v2
	v_readfirstlane_b32 s3, v3
	s_mul_i32 s2, s2, 4
	s_mul_i32 s3, s3, 4
	s_waitcnt vmcnt(1)
	v_readfirstlane_b32 s6, v4
	s_add_i32 s6, s6, 1
	s_cmp_lg_u32 s6, s2
	s_cbranch_scc1 .Lxb3_spin
	buffer_wbl2 sc1
	s_waitcnt vmcnt(0)
	v_mov_b32_e32 v0, 0x3000
	global_atomic_add v0, v1, s[98:99] offset:1024

; __device__ __forceinline__ unsigned xb_ld(unsigned* p)              { return __hip_atomic_load(p, __ATOMIC_RELAXED, __HIP_MEMORY_SCOPE_AGENT); }
; __device__ __forceinline__ unsigned xb_add(unsigned* p, unsigned v) { return __hip_atomic_fetch_add(p, v, __ATOMIC_RELAXED, __HIP_MEMORY_SCOPE_AGENT); }
; #define XB_SPIN(cond, bar) do { unsigned _sp = 0; while (cond) { __builtin_amdgcn_s_sleep(1); \
;     if ((++_sp & 255u) == 0u) { if (xb_ld(&(bar)[XB_TMO])) break; if (_sp > XB_SPIN_CAP) { atomicAdd(&(bar)[XB_TMO], 1u); break; } } } } while (0)
; __device__ __forceinline__ void xcd_barrier(const XcdBarrier& b) {
;     ...
;         const unsigned old = xb_add(&bar[XB_XSUB(b.x)], 1u);
;         const unsigned gen = old / nloc;
;         if (old + 1u == (gen + 1u) * nloc) {
;             __builtin_amdgcn_fence(__ATOMIC_RELEASE, "agent");
;             asm volatile("s_waitcnt vmcnt(0)" ::: "memory");
;             const unsigned og = xb_add(&bar[XB_TOP], 1u);
;             const unsigned tg = og / nx;
;             if (og + 1u == (tg + 1u) * nx) xb_add(&bar[XB_TOPGEN], 1u);
;             else XB_SPIN(xb_ld(&bar[XB_TOPGEN]) == tg, bar);
;             __builtin_amdgcn_fence(__ATOMIC_ACQUIRE, "agent");
;             xb_add(&bar[XB_XGEN(b.x)], 1u);
.LBB0_398:
	s_or_b64 exec, exec, s[8:9]
	s_waitcnt vmcnt(0)
	s_barrier
	s_mov_b64 s[0:1], exec
	v_readlane_b32 s2, v254, 2
	v_readlane_b32 s3, v254, 3
	s_and_b64 s[2:3], s[0:1], s[2:3]
	s_mov_b64 exec, s[2:3]
	s_cbranch_execz .LBB0_450
	v_readlane_b32 s98, v254, 5
	v_readlane_b32 s99, v254, 6
	v_readlane_b32 s6, v254, 1
	v_mov_b32_e32 v0, 0x23fc0
	s_waitcnt vmcnt(0) lgkmcnt(0)
	ds_read2_b32 v[2:3], v0 offset1:1
	s_lshl_b32 s6, s6, 8
	s_add_u32 s100, s98, s6
	s_addc_u32 s101, s99, 0
	v_mov_b32_e32 v0, 0x1000
	v_mov_b32_e32 v1, 1
	global_atomic_add v4, v0, v1, s[100:101] offset:1024 sc0
	buffer_inv sc1
	s_waitcnt lgkmcnt(0)
	v_readfirstlane_b32 s2, v2
	v_readfirstlane_b32 s3, v3
	s_mul_i32 s2, s2, 5
	s_mul_i32 s3, s3, 5
	s_waitcnt vmcnt(1)
	v_readfirstlane_b32 s6, v4
	s_add_i32 s6, s6, 1
	s_cmp_lg_u32 s6, s2
	s_cbranch_scc1 .Lxb4_spin
	buffer_wbl2 sc1
	s_waitcnt vmcnt(0)
	v_mov_b32_e32 v0, 0x3000
	global_atomic_add v0, v1, s[98:99] offset:1024

; __device__ __forceinline__ unsigned xb_ld(unsigned* p)              { return __hip_atomic_load(p, __ATOMIC_RELAXED, __HIP_MEMORY_SCOPE_AGENT); }
; __device__ __forceinline__ unsigned xb_add(unsigned* p, unsigned v) { return __hip_atomic_fetch_add(p, v, __ATOMIC_RELAXED, __HIP_MEMORY_SCOPE_AGENT); }
; #define XB_SPIN(cond, bar) do { unsigned _sp = 0; while (cond) { __builtin_amdgcn_s_sleep(1); \
;     if ((++_sp & 255u) == 0u) { if (xb_ld(&(bar)[XB_TMO])) break; if (_sp > XB_SPIN_CAP) { atomicAdd(&(bar)[XB_TMO], 1u); break; } } } } while (0)
; __device__ __forceinline__ void xcd_barrier(const XcdBarrier& b) {
;     ...
;         const unsigned old = xb_add(&bar[XB_XSUB(b.x)], 1u);
;         const unsigned gen = old / nloc;
;         if (old + 1u == (gen + 1u) * nloc) {
;             __builtin_amdgcn_fence(__ATOMIC_RELEASE, "agent");
;             asm volatile("s_waitcnt vmcnt(0)" ::: "memory");
;             const unsigned og = xb_add(&bar[XB_TOP], 1u);
;             const unsigned tg = og / nx;
;             if (og + 1u == (tg + 1u) * nx) xb_add(&bar[XB_TOPGEN], 1u);
;             else XB_SPIN(xb_ld(&bar[XB_TOPGEN]) == tg, bar);
;             __builtin_amdgcn_fence(__ATOMIC_ACQUIRE, "agent");
;             xb_add(&bar[XB_XGEN(b.x)], 1u);
.LBB0_530:
	s_waitcnt vmcnt(0)
	s_waitcnt vmcnt(0)
	s_barrier
	s_mov_b64 s[0:1], exec
	v_readlane_b32 s2, v254, 2
	v_readlane_b32 s3, v254, 3
	s_and_b64 s[2:3], s[0:1], s[2:3]
	s_mov_b64 exec, s[2:3]
	s_cbranch_execz .LBB0_582
	v_readlane_b32 s98, v254, 5
	v_readlane_b32 s99, v254, 6
	v_readlane_b32 s6, v254, 1
	v_mov_b32_e32 v0, 0x23fc0
	s_waitcnt vmcnt(0) lgkmcnt(0)
	ds_read2_b32 v[2:3], v0 offset1:1
	s_lshl_b32 s6, s6, 8
	s_add_u32 s100, s98, s6
	s_addc_u32 s101, s99, 0
	v_mov_b32_e32 v0, 0x1000
	v_mov_b32_e32 v1, 1
	global_atomic_add v4, v0, v1, s[100:101] offset:1024 sc0
	buffer_inv sc1
	s_waitcnt lgkmcnt(0)
	v_readfirstlane_b32 s2, v2
	v_readfirstlane_b32 s3, v3
	s_mul_i32 s2, s2, 6
	s_mul_i32 s3, s3, 6
	s_waitcnt vmcnt(1)
	v_readfirstlane_b32 s6, v4
	s_add_i32 s6, s6, 1
	s_cmp_lg_u32 s6, s2
	s_cbranch_scc1 .Lxb5_spin
	buffer_wbl2 sc1
	s_waitcnt vmcnt(0)
	v_mov_b32_e32 v0, 0x3000
	global_atomic_add v0, v1, s[98:99] offset:1024

; __device__ __forceinline__ unsigned xb_ld(unsigned* p)              { return __hip_atomic_load(p, __ATOMIC_RELAXED, __HIP_MEMORY_SCOPE_AGENT); }
; __device__ __forceinline__ unsigned xb_add(unsigned* p, unsigned v) { return __hip_atomic_fetch_add(p, v, __ATOMIC_RELAXED, __HIP_MEMORY_SCOPE_AGENT); }
; #define XB_SPIN(cond, bar) do { unsigned _sp = 0; while (cond) { __builtin_amdgcn_s_sleep(1); \
;     if ((++_sp & 255u) == 0u) { if (xb_ld(&(bar)[XB_TMO])) break; if (_sp > XB_SPIN_CAP) { atomicAdd(&(bar)[XB_TMO], 1u); break; } } } } while (0)
; __device__ __forceinline__ void xcd_barrier(const XcdBarrier& b) {
;     ...
;         const unsigned old = xb_add(&bar[XB_XSUB(b.x)], 1u);
;         const unsigned gen = old / nloc;
;         if (old + 1u == (gen + 1u) * nloc) {
;             __builtin_amdgcn_fence(__ATOMIC_RELEASE, "agent");
;             asm volatile("s_waitcnt vmcnt(0)" ::: "memory");
;             const unsigned og = xb_add(&bar[XB_TOP], 1u);
;             const unsigned tg = og / nx;
;             if (og + 1u == (tg + 1u) * nx) xb_add(&bar[XB_TOPGEN], 1u);
;             else XB_SPIN(xb_ld(&bar[XB_TOPGEN]) == tg, bar);
;             __builtin_amdgcn_fence(__ATOMIC_ACQUIRE, "agent");
;             xb_add(&bar[XB_XGEN(b.x)], 1u);
.LBB0_606:
	s_waitcnt vmcnt(0)
	s_barrier
	s_mov_b64 s[0:1], exec
	v_readlane_b32 s2, v254, 2
	v_readlane_b32 s3, v254, 3
	s_and_b64 s[2:3], s[0:1], s[2:3]
	s_mov_b64 exec, s[2:3]
	s_cbranch_execz .LBB0_658
	v_readlane_b32 s98, v254, 5
	v_readlane_b32 s99, v254, 6
	v_readlane_b32 s6, v254, 1
	v_mov_b32_e32 v0, 0x23fc0
	s_waitcnt vmcnt(0) lgkmcnt(0)
	ds_read2_b32 v[2:3], v0 offset1:1
	s_lshl_b32 s6, s6, 8
	s_add_u32 s100, s98, s6
	s_addc_u32 s101, s99, 0
	v_mov_b32_e32 v0, 0x1000
	v_mov_b32_e32 v1, 1
	global_atomic_add v4, v0, v1, s[100:101] offset:1024 sc0
	buffer_inv sc1
	s_waitcnt lgkmcnt(0)
	v_readfirstlane_b32 s2, v2
	v_readfirstlane_b32 s3, v3
	s_mul_i32 s2, s2, 7
	s_mul_i32 s3, s3, 7
	s_waitcnt vmcnt(1)
	v_readfirstlane_b32 s6, v4
	s_add_i32 s6, s6, 1
	s_cmp_lg_u32 s6, s2
	s_cbranch_scc1 .Lxb6_spin
	buffer_wbl2 sc1
	s_waitcnt vmcnt(0)
	v_mov_b32_e32 v0, 0x3000
	global_atomic_add v0, v1, s[98:99] offset:1024

;     __device__ __forceinline__ void run(const pg8::Unit& u, LAS unsigned char* lds, int wid, int lane) const {
;     ...
;             __builtin_amdgcn_fence(__ATOMIC_ACQUIRE, "agent"); }
;         asm volatile("s_waitcnt vmcnt(0) lgkmcnt(0)" ::: "memory"); __builtin_amdgcn_s_barrier(); asm volatile("" ::: "memory");
;         if (lane < 32) { const float* slot = xbuf + (size_t)(u.pm * 256 + row) * 4; float q = 0.f;
; #pragma unroll
;             for (int t = 0; t < 4; ++t) q += __hip_atomic_load(slot + t, __ATOMIC_RELAXED, __HIP_MEMORY_SCOPE_AGENT);
;             S[row] = 1.0f / sqrtf(q * (1.0f / 1024.0f) + EPS); }
.LBB0_705:
.LBB0_706:
	s_waitcnt vmcnt(0) lgkmcnt(0)
	s_barrier
	s_and_saveexec_b64 s[8:9], s[6:7]
	s_cbranch_execz .LBB0_708
	v_lshl_add_u64 v[0:1], v[0:1], 4, s[2:3]
	global_load_dword v3, v[0:1], off sc1
	global_load_dword v4, v[0:1], off offset:4 sc1
	global_load_dword v5, v[0:1], off offset:8 sc1
	s_nop 0
	global_load_dword v0, v[0:1], off offset:12 sc1
	v_mov_b32_e32 v1, 0x358637bd
	s_mov_b32 s2, 0xf800000
	s_waitcnt vmcnt(3)
	v_add_f32_e32 v3, 0, v3
	s_waitcnt vmcnt(2)
	v_add_f32_e32 v3, v3, v4
	s_waitcnt vmcnt(1)
	v_add_f32_e32 v3, v3, v5
	s_waitcnt vmcnt(0)
	v_add_f32_e32 v0, v3, v0
	v_fmac_f32_e32 v1, 0x3a800000, v0
	v_mul_f32_e32 v0, 0x4f800000, v1
	v_cmp_gt_f32_e32 vcc, s2, v1
	v_mov_b32_e32 v3, 0x260
	s_nop 0
	v_cndmask_b32_e32 v0, v1, v0, vcc
	v_sqrt_f32_e32 v1, v0
	s_nop 0
	v_add_u32_e32 v4, -1, v1
	v_add_u32_e32 v5, 1, v1
	v_fma_f32 v6, -v4, v1, v0
	v_fma_f32 v7, -v5, v1, v0
	v_cmp_ge_f32_e64 s[6:7], 0, v6
	s_nop 1
	v_cndmask_b32_e64 v1, v1, v4, s[6:7]
	v_cmp_lt_f32_e64 s[6:7], 0, v7
	s_nop 1
	v_cndmask_b32_e64 v1, v1, v5, s[6:7]
	v_mul_f32_e32 v4, 0x37800000, v1
	v_cndmask_b32_e32 v1, v1, v4, vcc
	v_cmp_class_f32_e32 vcc, v0, v3
	s_nop 1
	v_cndmask_b32_e32 v0, v1, v0, vcc
	v_div_scale_f32 v1, s[2:3], v0, v0, 1.0
	v_rcp_f32_e32 v3, v1
	v_div_scale_f32 v4, vcc, 1.0, v0, 1.0
	v_fma_f32 v5, -v1, v3, 1.0
	v_fmac_f32_e32 v3, v5, v3
	v_mul_f32_e32 v5, v4, v3
	v_fma_f32 v6, -v1, v5, v4
	v_fmac_f32_e32 v5, v6, v3
	v_fma_f32 v1, -v1, v5, v4
	v_div_fmas_f32 v1, v1, v3, v5
	v_div_fixup_f32 v0, v1, v0, 1.0
	v_lshl_add_u32 v1, v2, 2, 0
	ds_write_b32 v1, v0 offset:4096

; __device__ __forceinline__ unsigned xb_ld(unsigned* p)              { return __hip_atomic_load(p, __ATOMIC_RELAXED, __HIP_MEMORY_SCOPE_AGENT); }
; __device__ __forceinline__ unsigned xb_add(unsigned* p, unsigned v) { return __hip_atomic_fetch_add(p, v, __ATOMIC_RELAXED, __HIP_MEMORY_SCOPE_AGENT); }
; #define XB_SPIN(cond, bar) do { unsigned _sp = 0; while (cond) { __builtin_amdgcn_s_sleep(1); \
;     if ((++_sp & 255u) == 0u) { if (xb_ld(&(bar)[XB_TMO])) break; if (_sp > XB_SPIN_CAP) { atomicAdd(&(bar)[XB_TMO], 1u); break; } } } } while (0)
; __device__ __forceinline__ void xcd_barrier(const XcdBarrier& b) {
;     ...
;         const unsigned old = xb_add(&bar[XB_XSUB(b.x)], 1u);
;         const unsigned gen = old / nloc;
;         if (old + 1u == (gen + 1u) * nloc) {
;             __builtin_amdgcn_fence(__ATOMIC_RELEASE, "agent");
;             asm volatile("s_waitcnt vmcnt(0)" ::: "memory");
;             const unsigned og = xb_add(&bar[XB_TOP], 1u);
;             const unsigned tg = og / nx;
;             if (og + 1u == (tg + 1u) * nx) xb_add(&bar[XB_TOPGEN], 1u);
;             else XB_SPIN(xb_ld(&bar[XB_TOPGEN]) == tg, bar);
;             __builtin_amdgcn_fence(__ATOMIC_ACQUIRE, "agent");
;             xb_add(&bar[XB_XGEN(b.x)], 1u);
.LBB0_709:
	s_waitcnt vmcnt(0)
	s_barrier
	s_mov_b64 s[0:1], exec
	v_readlane_b32 s2, v254, 2
	v_readlane_b32 s3, v254, 3
	s_and_b64 s[2:3], s[0:1], s[2:3]
	s_mov_b64 exec, s[2:3]
	s_cbranch_execz .LBB0_761
	v_readlane_b32 s98, v254, 5
	v_readlane_b32 s99, v254, 6
	v_readlane_b32 s6, v254, 1
	v_mov_b32_e32 v0, 0x23fc0
	s_waitcnt vmcnt(0) lgkmcnt(0)
	ds_read2_b32 v[2:3], v0 offset1:1
	s_lshl_b32 s6, s6, 8
	s_add_u32 s100, s98, s6
	s_addc_u32 s101, s99, 0
	v_mov_b32_e32 v0, 0x1000
	v_mov_b32_e32 v1, 1
	global_atomic_add v4, v0, v1, s[100:101] offset:1024 sc0
	buffer_inv sc1
	s_waitcnt lgkmcnt(0)
	v_readfirstlane_b32 s2, v2
	v_readfirstlane_b32 s3, v3
	s_mul_i32 s2, s2, 8
	s_mul_i32 s3, s3, 8
	s_waitcnt vmcnt(1)
	v_readfirstlane_b32 s6, v4
	s_add_i32 s6, s6, 1
	s_cmp_lg_u32 s6, s2
	s_cbranch_scc1 .Lxb7_spin
	buffer_wbl2 sc1
	s_waitcnt vmcnt(0)
	v_mov_b32_e32 v0, 0x3000
	global_atomic_add v0, v1, s[98:99] offset:1024

; __device__ __forceinline__ unsigned xb_ld(unsigned* p)              { return __hip_atomic_load(p, __ATOMIC_RELAXED, __HIP_MEMORY_SCOPE_AGENT); }
; __device__ __forceinline__ unsigned xb_add(unsigned* p, unsigned v) { return __hip_atomic_fetch_add(p, v, __ATOMIC_RELAXED, __HIP_MEMORY_SCOPE_AGENT); }
; #define XB_SPIN(cond, bar) do { unsigned _sp = 0; while (cond) { __builtin_amdgcn_s_sleep(1); \
;     if ((++_sp & 255u) == 0u) { if (xb_ld(&(bar)[XB_TMO])) break; if (_sp > XB_SPIN_CAP) { atomicAdd(&(bar)[XB_TMO], 1u); break; } } } } while (0)
; __device__ __forceinline__ void xcd_barrier(const XcdBarrier& b) {
;     ...
;         const unsigned old = xb_add(&bar[XB_XSUB(b.x)], 1u);
;         const unsigned gen = old / nloc;
;         if (old + 1u == (gen + 1u) * nloc) {
;             __builtin_amdgcn_fence(__ATOMIC_RELEASE, "agent");
;             asm volatile("s_waitcnt vmcnt(0)" ::: "memory");
;             const unsigned og = xb_add(&bar[XB_TOP], 1u);
;             const unsigned tg = og / nx;
;             if (og + 1u == (tg + 1u) * nx) xb_add(&bar[XB_TOPGEN], 1u);
;             else XB_SPIN(xb_ld(&bar[XB_TOPGEN]) == tg, bar);
;             __builtin_amdgcn_fence(__ATOMIC_ACQUIRE, "agent");
;             xb_add(&bar[XB_XGEN(b.x)], 1u);
.LBB0_856:
	s_waitcnt vmcnt(0)
	s_waitcnt vmcnt(0) lgkmcnt(0)
	s_barrier
	s_mov_b64 s[0:1], exec
	v_readlane_b32 s2, v254, 2
	v_readlane_b32 s3, v254, 3
	s_and_b64 s[2:3], s[0:1], s[2:3]
	s_mov_b64 exec, s[2:3]
	s_cbranch_execz .LBB0_908
	v_readlane_b32 s98, v254, 5
	v_readlane_b32 s99, v254, 6
	v_readlane_b32 s6, v254, 1
	v_mov_b32_e32 v0, 0x23fc0
	s_waitcnt vmcnt(0) lgkmcnt(0)
	ds_read2_b32 v[2:3], v0 offset1:1
	s_lshl_b32 s6, s6, 8
	s_add_u32 s100, s98, s6
	s_addc_u32 s101, s99, 0
	v_mov_b32_e32 v0, 0x1000
	v_mov_b32_e32 v1, 1
	global_atomic_add v4, v0, v1, s[100:101] offset:1024 sc0
	buffer_inv sc1
	s_waitcnt lgkmcnt(0)
	v_readfirstlane_b32 s2, v2
	v_readfirstlane_b32 s3, v3
	s_mul_i32 s2, s2, 9
	s_mul_i32 s3, s3, 9
	s_waitcnt vmcnt(1)
	v_readfirstlane_b32 s6, v4
	s_add_i32 s6, s6, 1
	s_cmp_lg_u32 s6, s2
	s_cbranch_scc1 .Lxb8_spin
	buffer_wbl2 sc1
	s_waitcnt vmcnt(0)
	v_mov_b32_e32 v0, 0x3000
	global_atomic_add v0, v1, s[98:99] offset:1024

;     __device__ __forceinline__ void run(const pg8::Unit& u, LAS unsigned char* lds, int wid, int lane) const {
;     ...
;             __builtin_amdgcn_fence(__ATOMIC_ACQUIRE, "agent"); }
;         asm volatile("s_waitcnt vmcnt(0) lgkmcnt(0)" ::: "memory"); __builtin_amdgcn_s_barrier(); asm volatile("" ::: "memory");
;         if (lane < 32) { const float* slot = xbuf + (size_t)(u.pm * 256 + row) * 4; float q = 0.f;
; #pragma unroll
;             for (int t = 0; t < 4; ++t) q += __hip_atomic_load(slot + t, __ATOMIC_RELAXED, __HIP_MEMORY_SCOPE_AGENT);
;             S[row] = 1.0f / sqrtf(q * (1.0f / 1024.0f) + EPS); }
.LBB0_955:
.LBB0_956:
	s_waitcnt vmcnt(0) lgkmcnt(0)
	s_barrier
	s_and_saveexec_b64 s[4:5], s[0:1]
	s_cbranch_execz .LBB0_958
	v_lshl_add_u64 v[0:1], v[0:1], 4, s[2:3]
	global_load_dword v3, v[0:1], off sc1
	global_load_dword v4, v[0:1], off offset:4 sc1
	global_load_dword v5, v[0:1], off offset:8 sc1
	s_nop 0
	global_load_dword v0, v[0:1], off offset:12 sc1
	v_mov_b32_e32 v1, 0x358637bd
	s_mov_b32 s0, 0xf800000
	s_waitcnt vmcnt(3)
	v_add_f32_e32 v3, 0, v3
	s_waitcnt vmcnt(2)
	v_add_f32_e32 v3, v3, v4
	s_waitcnt vmcnt(1)
	v_add_f32_e32 v3, v3, v5
	s_waitcnt vmcnt(0)
	v_add_f32_e32 v0, v3, v0
	v_fmac_f32_e32 v1, 0x3a800000, v0
	v_mul_f32_e32 v0, 0x4f800000, v1
	v_cmp_gt_f32_e32 vcc, s0, v1
	v_mov_b32_e32 v3, 0x260
	s_nop 0
	v_cndmask_b32_e32 v0, v1, v0, vcc
	v_sqrt_f32_e32 v1, v0
	s_nop 0
	v_add_u32_e32 v4, -1, v1
	v_add_u32_e32 v5, 1, v1
	v_fma_f32 v6, -v4, v1, v0
	v_fma_f32 v7, -v5, v1, v0
	v_cmp_ge_f32_e64 s[0:1], 0, v6
	s_nop 1
	v_cndmask_b32_e64 v1, v1, v4, s[0:1]
	v_cmp_lt_f32_e64 s[0:1], 0, v7
	s_nop 1
	v_cndmask_b32_e64 v1, v1, v5, s[0:1]
	v_mul_f32_e32 v4, 0x37800000, v1
	v_cndmask_b32_e32 v1, v1, v4, vcc
	v_cmp_class_f32_e32 vcc, v0, v3
	s_nop 1
	v_cndmask_b32_e32 v0, v1, v0, vcc
	v_div_scale_f32 v1, s[0:1], v0, v0, 1.0
	v_rcp_f32_e32 v3, v1
	v_div_scale_f32 v4, vcc, 1.0, v0, 1.0
	v_fma_f32 v5, -v1, v3, 1.0
	v_fmac_f32_e32 v3, v5, v3
	v_mul_f32_e32 v5, v4, v3
	v_fma_f32 v6, -v1, v5, v4
	v_fmac_f32_e32 v5, v6, v3
	v_fma_f32 v1, -v1, v5, v4
	v_div_fmas_f32 v1, v1, v3, v5
	v_div_fixup_f32 v0, v1, v0, 1.0
	v_lshl_add_u32 v1, v2, 2, 0
	ds_write_b32 v1, v0 offset:4096
